# phase 2: half of every XCD's workgroups run 1 attention round, then their conv tiles, then 3 attention rounds (the others: 4 rounds then conv), so HBM-bound conv overlaps the L2-bound attention gather
# speedup vs baseline: 1.0187x; 1.0083x over previous
.LBB0_1072:
	s_cmp_gt_i32 s66, 1
	s_mov_b64 s[0:1], -1
	s_cbranch_scc0 .LBB0_1115
	s_mov_b32 s98, 0x400
	s_bitcmp1_b32 s99, 3
	s_cselect_b32 s98, 0x100, s98
.Lp2_na:
	s_mov_b64 exec, -1
	v_writelane_b32 v245, s0, 0
	v_writelane_b32 v245, s1, 1
	v_writelane_b32 v245, s2, 2
	v_writelane_b32 v245, s3, 3
	v_writelane_b32 v245, s4, 4
	v_writelane_b32 v245, s5, 5
	v_writelane_b32 v245, s6, 6
	v_writelane_b32 v245, s7, 7
	v_writelane_b32 v245, s8, 8
	v_writelane_b32 v245, s9, 9
	v_writelane_b32 v245, s10, 10
	v_writelane_b32 v245, s11, 11
	v_writelane_b32 v245, s12, 12
	v_writelane_b32 v245, s13, 13
	v_writelane_b32 v245, s14, 14
	v_writelane_b32 v245, s15, 15
	v_writelane_b32 v245, s16, 16
	v_writelane_b32 v245, s17, 17
	v_writelane_b32 v245, s18, 18
	v_writelane_b32 v245, s19, 19
	v_writelane_b32 v245, s20, 20
	v_writelane_b32 v245, s21, 21
	v_writelane_b32 v245, s22, 22
	v_writelane_b32 v245, s23, 23
	v_writelane_b32 v245, s24, 24
	v_writelane_b32 v245, s25, 25
	v_writelane_b32 v245, s26, 26
	v_writelane_b32 v245, s27, 27
	v_writelane_b32 v245, s28, 28
	v_writelane_b32 v245, s29, 29
	v_writelane_b32 v245, s30, 30
	v_writelane_b32 v245, s31, 31
	v_writelane_b32 v245, s32, 32
	v_writelane_b32 v245, s33, 33
	v_writelane_b32 v245, s34, 34
	v_writelane_b32 v245, s35, 35
	v_writelane_b32 v245, s36, 36
	v_writelane_b32 v245, s37, 37
	v_writelane_b32 v245, s38, 38
	v_writelane_b32 v245, s39, 39
	v_writelane_b32 v245, s40, 40
	v_writelane_b32 v245, s41, 41
	v_writelane_b32 v245, s42, 42
	v_writelane_b32 v245, s43, 43
	v_writelane_b32 v245, s44, 44
	v_writelane_b32 v245, s45, 45
	v_writelane_b32 v245, s46, 46
	v_writelane_b32 v245, s47, 47
	v_writelane_b32 v245, s48, 48
	v_writelane_b32 v245, s49, 49
	v_writelane_b32 v245, s50, 50
	v_writelane_b32 v245, s51, 51
	v_writelane_b32 v245, s52, 52
	v_writelane_b32 v245, s53, 53
	v_writelane_b32 v245, s54, 54
	v_writelane_b32 v245, s55, 55
	v_writelane_b32 v245, s56, 56
	v_writelane_b32 v245, s57, 57
	v_writelane_b32 v245, s58, 58
	v_writelane_b32 v245, s59, 59
	v_writelane_b32 v245, s60, 60
	v_writelane_b32 v245, s61, 61
	v_writelane_b32 v245, s62, 62
	v_writelane_b32 v245, s63, 63
	v_writelane_b32 v244, s64, 0
	v_writelane_b32 v244, s65, 1
	v_writelane_b32 v244, s66, 2
	v_writelane_b32 v244, s67, 3
	v_writelane_b32 v244, s68, 4
	v_writelane_b32 v244, s69, 5
	v_writelane_b32 v244, s70, 6
	v_writelane_b32 v244, s71, 7
	v_writelane_b32 v244, s72, 8
	v_writelane_b32 v244, s73, 9
	v_writelane_b32 v244, s74, 10
	v_writelane_b32 v244, s75, 11
	v_writelane_b32 v244, s76, 12
	v_writelane_b32 v244, s77, 13
	v_writelane_b32 v244, s78, 14
	v_writelane_b32 v244, s79, 15
	v_lshrrev_b32_e32 v235, 6, v225
	v_and_b32_e32 v246, 63, v225
	s_load_dwordx2 s[10:11], s[100:101], 0xb0
	s_load_dwordx2 s[12:13], s[100:101], 0x28
	v_readfirstlane_b32 s4, v235
	v_and_b32_e32 v236, 15, v246
	v_lshrrev_b32_e32 v237, 4, v246
	s_nop 3
	s_and_b32 s5, s4, 3
	s_lshr_b32 s6, s4, 2
	s_lshl_b32 s7, s99, 1
	s_add_u32 s7, s7, s6
	s_lshl_b32 s8, s5, 4
	s_sub_i32 s8, s8, 8
	s_max_i32 s8, s8, 0
	s_min_i32 s8, s8, 32
	s_lshl_b32 s9, s5, 4
	v_lshrrev_b32_e32 v240, 2, v236
	v_and_b32_e32 v241, 3, v236
	v_lshl_add_u32 v240, v240, 3, v241
	v_lshlrev_b32_e32 v240, 10, v240
	v_lshl_add_u32 v218, v237, 4, v240
	v_add_u32_e32 v219, 0x1000, v218
	v_lshlrev_b32_e32 v240, 12, v236
	v_lshl_add_u32 v220, v237, 4, v240
	v_lshlrev_b32_e32 v240, 10, v236
	v_lshl_add_u32 v221, v237, 4, v240
	v_mul_u32_u24_e32 v240, 0xc00, v236
	v_lshl_add_u32 v222, v237, 3, v240
	v_xor_b32_e32 v223, 16, v246
	v_lshlrev_b32_e32 v223, 2, v223
	v_xor_b32_e32 v232, 32, v246
	v_lshlrev_b32_e32 v232, 2, v232
	s_lshr_b32 s36, s8, 3
	v_add_u32_e32 v136, s36, v237
	v_xor_b32_e32 v136, v136, v236
	v_lshlrev_b32_e32 v136, 4, v136
	v_lshl_or_b32 v136, v236, 10, v136
	s_lshl_b32 s36, s6, 16
	v_or_b32_e32 v136, s36, v136
	s_lshl_b32 s39, s5, 14
	s_add_u32 s39, s39, s36
	s_add_u32 s39, s39, 16
	v_add_u32_e32 v240, s9, v236
	v_lshl_add_u32 v241, v237, 3, s8
	v_sub_u32_e32 v235, v241, v240
	v_subrev_u32_e32 v240, 8, v240
	v_med3_i32 v240, v240, 0, 48
	v_sub_u32_e32 v241, v241, v240
	v_add_u32_e32 v240, 0, v235
	v_med3_i32 v240, v240, -15, 15
	v_add_u32_e32 v240, 15, v240
	v_lshlrev_b32_e32 v210, 2, v240
	v_add_u32_e32 v240, 0, v241
	v_cmp_gt_u32_e64 s[40:41], 16, v240
	v_add_u32_e32 v240, 1, v235
	v_med3_i32 v240, v240, -15, 15
	v_add_u32_e32 v240, 15, v240
	v_lshlrev_b32_e32 v211, 2, v240
	v_add_u32_e32 v240, 1, v241
	v_cmp_gt_u32_e64 s[42:43], 16, v240
	v_add_u32_e32 v240, 2, v235
	v_med3_i32 v240, v240, -15, 15
	v_add_u32_e32 v240, 15, v240
	v_lshlrev_b32_e32 v212, 2, v240
	v_add_u32_e32 v240, 2, v241
	v_cmp_gt_u32_e64 s[44:45], 16, v240
	v_add_u32_e32 v240, 3, v235
	v_med3_i32 v240, v240, -15, 15
	v_add_u32_e32 v240, 15, v240
	v_lshlrev_b32_e32 v213, 2, v240
	v_add_u32_e32 v240, 3, v241
	v_cmp_gt_u32_e64 s[46:47], 16, v240
	v_add_u32_e32 v240, 4, v235
	v_med3_i32 v240, v240, -15, 15
	v_add_u32_e32 v240, 15, v240
	v_lshlrev_b32_e32 v214, 2, v240
	v_add_u32_e32 v240, 4, v241
	v_cmp_gt_u32_e64 s[48:49], 16, v240
	v_add_u32_e32 v240, 5, v235
	v_med3_i32 v240, v240, -15, 15
	v_add_u32_e32 v240, 15, v240
	v_lshlrev_b32_e32 v215, 2, v240
	v_add_u32_e32 v240, 5, v241
	v_cmp_gt_u32_e64 s[50:51], 16, v240
	v_add_u32_e32 v240, 6, v235
	v_med3_i32 v240, v240, -15, 15
	v_add_u32_e32 v240, 15, v240
	v_lshlrev_b32_e32 v216, 2, v240
	v_add_u32_e32 v240, 6, v241
	v_cmp_gt_u32_e64 s[52:53], 16, v240
	v_add_u32_e32 v240, 7, v235
	v_med3_i32 v240, v240, -15, 15
	v_add_u32_e32 v240, 15, v240
	v_lshlrev_b32_e32 v217, 2, v240
	v_add_u32_e32 v240, 7, v241
	v_cmp_gt_u32_e64 s[54:55], 16, v240
	s_waitcnt lgkmcnt(0)
	s_and_b32 s14, s98, 0xff
	s_lshl_b32 s36, s14, 9
	s_add_u32 s7, s7, s36
	s_and_b32 s15, s7, 7
	s_bfe_u32 s16, s7, 0x50003
	s_lshr_b32 s17, s7, 8
	s_sub_i32 s18, s16, 4
	s_max_i32 s18, s18, 0
	s_min_i32 s18, s18, 24
	s_lshl_b32 s19, s17, 11
	s_lshl_b32 s20, s18, 6
	s_add_u32 s20, s20, s19
	s_add_u32 s20, s20, s8
	s_lshl_b32 s21, s16, 6
	s_add_u32 s21, s21, s19
	s_add_u32 s21, s21, s9
	s_lshl_b32 s22, s15, 7
	s_lshl_b32 s23, s20, 10
	s_add_u32 s23, s23, s22
	s_add_u32 s0, s10, 0x5200000
	s_addc_u32 s1, s11, 0
	s_add_u32 s0, s0, s23
	s_addc_u32 s1, s1, 0
	s_lshl_b32 s23, s21, 10
	s_add_u32 s23, s23, s22
	s_add_u32 s2, s10, 0x4200000
	s_addc_u32 s3, s11, 0
	s_add_u32 s2, s2, s23
	s_addc_u32 s3, s3, 0
	global_load_dwordx4 v[0:3], v221, s[2:3]
	global_load_dwordx4 v[4:7], v221, s[2:3] offset:64
	global_load_dwordx4 v[72:75], v218, s[0:1]
	global_load_dwordx4 v[76:79], v218, s[0:1] offset:64
	global_load_dwordx4 v[80:83], v219, s[0:1]
	global_load_dwordx4 v[84:87], v219, s[0:1] offset:64
	s_add_u32 s0, s0, 0x10000
	s_addc_u32 s1, s1, 0
	global_load_dwordx4 v[88:91], v218, s[0:1]
	global_load_dwordx4 v[92:95], v218, s[0:1] offset:64
	global_load_dwordx4 v[96:99], v219, s[0:1]
	global_load_dwordx4 v[100:103], v219, s[0:1] offset:64
	s_add_u32 s0, s0, 0x10000
	s_addc_u32 s1, s1, 0
	global_load_dwordx4 v[104:107], v218, s[0:1]
	global_load_dwordx4 v[108:111], v218, s[0:1] offset:64
	global_load_dwordx4 v[112:115], v219, s[0:1]
	global_load_dwordx4 v[116:119], v219, s[0:1] offset:64
	s_add_u32 s0, s0, 0x10000
	s_addc_u32 s1, s1, 0
	global_load_dwordx4 v[120:123], v218, s[0:1]
	global_load_dwordx4 v[124:127], v218, s[0:1] offset:64
	global_load_dwordx4 v[128:131], v219, s[0:1]
	global_load_dwordx4 v[132:135], v219, s[0:1] offset:64
	s_add_u32 s0, s0, 0x10000
	s_addc_u32 s1, s1, 0
	global_load_dwordx4 v[146:149], v218, s[0:1]
	global_load_dwordx4 v[150:153], v218, s[0:1] offset:64
	global_load_dwordx4 v[154:157], v219, s[0:1]
	global_load_dwordx4 v[158:161], v219, s[0:1] offset:64
	s_add_u32 s0, s0, 0x10000
	s_addc_u32 s1, s1, 0
	global_load_dwordx4 v[162:165], v218, s[0:1]
	global_load_dwordx4 v[166:169], v218, s[0:1] offset:64
	global_load_dwordx4 v[170:173], v219, s[0:1]
	global_load_dwordx4 v[174:177], v219, s[0:1] offset:64
	s_add_u32 s0, s0, 0x10000
	s_addc_u32 s1, s1, 0
.Lna_tile:
	s_and_b32 s15, s7, 7
	s_bfe_u32 s16, s7, 0x50003
	s_lshr_b32 s17, s7, 8
	s_sub_i32 s18, s16, 4
	s_max_i32 s18, s18, 0
	s_min_i32 s18, s18, 24
	s_lshl_b32 s19, s17, 11
	s_lshl_b32 s20, s18, 6
	s_add_u32 s20, s20, s19
	s_add_u32 s20, s20, s8
	s_lshl_b32 s21, s16, 6
	s_add_u32 s21, s21, s19
	s_add_u32 s21, s21, s9
	s_lshl_b32 s22, s15, 7
	s_lshl_b32 s23, s17, 3
	s_add_u32 s23, s23, s15
	s_lshl_b32 s23, s23, 18
	s_lshl_b32 s24, s5, 16
	s_add_u32 s23, s23, s24
	s_lshl_b32 s24, s18, 7
	s_add_u32 s23, s23, s24
	s_add_u32 s24, s10, 0x6200000
	s_addc_u32 s25, s11, 0
	s_add_u32 s24, s24, s23
	s_addc_u32 s25, s25, 0
	s_mul_i32 s23, s21, 0xc00
	s_add_u32 s23, s23, s22
	s_add_u32 s32, s10, 0xc200000
	s_addc_u32 s33, s11, 0
	s_add_u32 s32, s32, s23
	s_addc_u32 s33, s33, 0
	s_mul_i32 s23, s15, 465
	s_sub_i32 s34, s18, s16
	s_add_i32 s34, s34, 7
	s_mul_i32 s34, s34, 31
	s_add_u32 s23, s23, s34
	s_lshl_b32 s23, s23, 2
	s_add_u32 s34, s12, s23
	s_addc_u32 s35, s13, 0
	s_barrier
	global_load_dword v8, v210, s[34:35]
	global_load_dword v9, v211, s[34:35]
	global_load_dword v10, v212, s[34:35]
	global_load_dword v11, v213, s[34:35]
	global_load_dword v12, v214, s[34:35]
	global_load_dword v13, v215, s[34:35]
	global_load_dword v14, v216, s[34:35]
	global_load_dword v15, v217, s[34:35]
	global_load_dword v16, v210, s[34:35] offset:124
	global_load_dword v17, v211, s[34:35] offset:124
	global_load_dword v18, v212, s[34:35] offset:124
	global_load_dword v19, v213, s[34:35] offset:124
	global_load_dword v20, v214, s[34:35] offset:124
	global_load_dword v21, v215, s[34:35] offset:124
	global_load_dword v22, v216, s[34:35] offset:124
	global_load_dword v23, v217, s[34:35] offset:124
	global_load_dword v24, v210, s[34:35] offset:248
	global_load_dword v25, v211, s[34:35] offset:248
	global_load_dword v26, v212, s[34:35] offset:248
	global_load_dword v27, v213, s[34:35] offset:248
	global_load_dword v28, v214, s[34:35] offset:248
	global_load_dword v29, v215, s[34:35] offset:248
	global_load_dword v30, v216, s[34:35] offset:248
	global_load_dword v31, v217, s[34:35] offset:248
	global_load_dword v32, v210, s[34:35] offset:372
	global_load_dword v33, v211, s[34:35] offset:372
	global_load_dword v34, v212, s[34:35] offset:372
	global_load_dword v35, v213, s[34:35] offset:372
	global_load_dword v36, v214, s[34:35] offset:372
	global_load_dword v37, v215, s[34:35] offset:372
	global_load_dword v38, v216, s[34:35] offset:372
	global_load_dword v39, v217, s[34:35] offset:372
	global_load_dword v40, v210, s[34:35] offset:496
	global_load_dword v41, v211, s[34:35] offset:496
	global_load_dword v42, v212, s[34:35] offset:496
	global_load_dword v43, v213, s[34:35] offset:496
	global_load_dword v44, v214, s[34:35] offset:496
	global_load_dword v45, v215, s[34:35] offset:496
	global_load_dword v46, v216, s[34:35] offset:496
	global_load_dword v47, v217, s[34:35] offset:496
	global_load_dword v48, v210, s[34:35] offset:620
	global_load_dword v49, v211, s[34:35] offset:620
	global_load_dword v50, v212, s[34:35] offset:620
	global_load_dword v51, v213, s[34:35] offset:620
	global_load_dword v52, v214, s[34:35] offset:620
	global_load_dword v53, v215, s[34:35] offset:620
	global_load_dword v54, v216, s[34:35] offset:620
	global_load_dword v55, v217, s[34:35] offset:620
	global_load_dword v56, v210, s[34:35] offset:744
	global_load_dword v57, v211, s[34:35] offset:744
	global_load_dword v58, v212, s[34:35] offset:744
	global_load_dword v59, v213, s[34:35] offset:744
	global_load_dword v60, v214, s[34:35] offset:744
	global_load_dword v61, v215, s[34:35] offset:744
	global_load_dword v62, v216, s[34:35] offset:744
	global_load_dword v63, v217, s[34:35] offset:744
	global_load_dword v64, v210, s[34:35] offset:868
	global_load_dword v65, v211, s[34:35] offset:868
	global_load_dword v66, v212, s[34:35] offset:868
	global_load_dword v67, v213, s[34:35] offset:868
	global_load_dword v68, v214, s[34:35] offset:868
	global_load_dword v69, v215, s[34:35] offset:868
	global_load_dword v70, v216, s[34:35] offset:868
	global_load_dword v71, v217, s[34:35] offset:868
	s_mov_b32 s26, s39
	v_xor_b32_e32 v137, 0, v246
	s_mov_b32 m0, s26
	v_lshlrev_b32_e32 v137, 4, v137
	global_load_lds_dwordx4 v137, s[24:25]
	s_add_u32 s24, s24, 0x1000
	s_addc_u32 s25, s25, 0
	s_add_u32 s26, s26, 0x400
	v_xor_b32_e32 v137, 1, v246
	s_mov_b32 m0, s26
	v_lshlrev_b32_e32 v137, 4, v137
	global_load_lds_dwordx4 v137, s[24:25]
	s_add_u32 s24, s24, 0x1000
	s_addc_u32 s25, s25, 0
	s_add_u32 s26, s26, 0x400
	v_xor_b32_e32 v137, 2, v246
	s_mov_b32 m0, s26
	v_lshlrev_b32_e32 v137, 4, v137
	global_load_lds_dwordx4 v137, s[24:25]
	s_add_u32 s24, s24, 0x1000
	s_addc_u32 s25, s25, 0
	s_add_u32 s26, s26, 0x400
	v_xor_b32_e32 v137, 3, v246
	s_mov_b32 m0, s26
	v_lshlrev_b32_e32 v137, 4, v137
	global_load_lds_dwordx4 v137, s[24:25]
	s_add_u32 s24, s24, 0x1000
	s_addc_u32 s25, s25, 0
	s_add_u32 s26, s26, 0x400
	v_xor_b32_e32 v137, 4, v246
	s_mov_b32 m0, s26
	v_lshlrev_b32_e32 v137, 4, v137
	global_load_lds_dwordx4 v137, s[24:25]
	s_add_u32 s24, s24, 0x1000
	s_addc_u32 s25, s25, 0
	s_add_u32 s26, s26, 0x400
	v_xor_b32_e32 v137, 5, v246
	s_mov_b32 m0, s26
	v_lshlrev_b32_e32 v137, 4, v137
	global_load_lds_dwordx4 v137, s[24:25]
	s_add_u32 s24, s24, 0x1000
	s_addc_u32 s25, s25, 0
	s_add_u32 s26, s26, 0x400
	v_xor_b32_e32 v137, 6, v246
	s_mov_b32 m0, s26
	v_lshlrev_b32_e32 v137, 4, v137
	global_load_lds_dwordx4 v137, s[24:25]
	s_add_u32 s24, s24, 0x1000
	s_addc_u32 s25, s25, 0
	s_add_u32 s26, s26, 0x400
	v_xor_b32_e32 v137, 7, v246
	s_mov_b32 m0, s26
	v_lshlrev_b32_e32 v137, 4, v137
	global_load_lds_dwordx4 v137, s[24:25]
	s_add_u32 s24, s24, 0x1000
	s_addc_u32 s25, s25, 0
	s_add_u32 s26, s26, 0x400
	v_xor_b32_e32 v137, 8, v246
	s_mov_b32 m0, s26
	v_lshlrev_b32_e32 v137, 4, v137
	global_load_lds_dwordx4 v137, s[24:25]
	s_add_u32 s24, s24, 0x1000
	s_addc_u32 s25, s25, 0
	s_add_u32 s26, s26, 0x400
	v_xor_b32_e32 v137, 9, v246
	s_mov_b32 m0, s26
	v_lshlrev_b32_e32 v137, 4, v137
	global_load_lds_dwordx4 v137, s[24:25]
	s_add_u32 s24, s24, 0x1000
	s_addc_u32 s25, s25, 0
	s_add_u32 s26, s26, 0x400
	v_xor_b32_e32 v137, 10, v246
	s_mov_b32 m0, s26
	v_lshlrev_b32_e32 v137, 4, v137
	global_load_lds_dwordx4 v137, s[24:25]
	s_add_u32 s24, s24, 0x1000
	s_addc_u32 s25, s25, 0
	s_add_u32 s26, s26, 0x400
	v_xor_b32_e32 v137, 11, v246
	s_mov_b32 m0, s26
	v_lshlrev_b32_e32 v137, 4, v137
	global_load_lds_dwordx4 v137, s[24:25]
	s_add_u32 s24, s24, 0x1000
	s_addc_u32 s25, s25, 0
	s_add_u32 s26, s26, 0x400
	v_xor_b32_e32 v137, 12, v246
	s_mov_b32 m0, s26
	v_lshlrev_b32_e32 v137, 4, v137
	global_load_lds_dwordx4 v137, s[24:25]
	s_add_u32 s24, s24, 0x1000
	s_addc_u32 s25, s25, 0
	s_add_u32 s26, s26, 0x400
	v_xor_b32_e32 v137, 13, v246
	s_mov_b32 m0, s26
	v_lshlrev_b32_e32 v137, 4, v137
	global_load_lds_dwordx4 v137, s[24:25]
	s_add_u32 s24, s24, 0x1000
	s_addc_u32 s25, s25, 0
	s_add_u32 s26, s26, 0x400
	v_xor_b32_e32 v137, 14, v246
	s_mov_b32 m0, s26
	v_lshlrev_b32_e32 v137, 4, v137
	global_load_lds_dwordx4 v137, s[24:25]
	s_add_u32 s24, s24, 0x1000
	s_addc_u32 s25, s25, 0
	s_add_u32 s26, s26, 0x400
	v_xor_b32_e32 v137, 15, v246
	s_mov_b32 m0, s26
	v_lshlrev_b32_e32 v137, 4, v137
	global_load_lds_dwordx4 v137, s[24:25]
	s_add_u32 s24, s24, 0x1000
	s_addc_u32 s25, s25, 0
	s_add_u32 s26, s26, 0x400
	v_mov_b32_e32 v178, 0
	v_mov_b32_e32 v179, 0
	v_mov_b32_e32 v180, 0
	v_mov_b32_e32 v181, 0
	v_mov_b32_e32 v182, 0
	v_mov_b32_e32 v183, 0
	v_mov_b32_e32 v184, 0
	v_mov_b32_e32 v185, 0
	v_mov_b32_e32 v186, 0
	v_mov_b32_e32 v187, 0
	v_mov_b32_e32 v188, 0
	v_mov_b32_e32 v189, 0
	v_mov_b32_e32 v190, 0
	v_mov_b32_e32 v191, 0
	v_mov_b32_e32 v192, 0
	v_mov_b32_e32 v193, 0
	s_waitcnt vmcnt(63)
	v_mfma_f32_16x16x32_bf16 v[194:197], v[72:75], v[0:3], 0
	v_mfma_f32_16x16x32_bf16 v[198:201], v[80:83], v[0:3], 0
	v_mfma_f32_16x16x32_bf16 v[194:197], v[76:79], v[4:7], v[194:197]
	v_mfma_f32_16x16x32_bf16 v[198:201], v[84:87], v[4:7], v[198:201]
	global_load_dwordx4 v[72:75], v218, s[0:1]
	global_load_dwordx4 v[76:79], v218, s[0:1] offset:64
	global_load_dwordx4 v[80:83], v219, s[0:1]
	global_load_dwordx4 v[84:87], v219, s[0:1] offset:64
	s_add_u32 s0, s0, 0x10000
	s_addc_u32 s1, s1, 0
	s_waitcnt vmcnt(63)
	v_mfma_f32_16x16x32_bf16 v[202:205], v[88:91], v[0:3], 0
	v_mfma_f32_16x16x32_bf16 v[206:209], v[96:99], v[0:3], 0
	v_mfma_f32_16x16x32_bf16 v[202:205], v[92:95], v[4:7], v[202:205]
	v_mfma_f32_16x16x32_bf16 v[206:209], v[100:103], v[4:7], v[206:209]
	global_load_dwordx4 v[88:91], v218, s[0:1]
	global_load_dwordx4 v[92:95], v218, s[0:1] offset:64
	global_load_dwordx4 v[96:99], v219, s[0:1]
	global_load_dwordx4 v[100:103], v219, s[0:1] offset:64
	s_add_u32 s0, s0, 0x10000
	s_addc_u32 s1, s1, 0
	s_waitcnt vmcnt(63)
	v_fmamk_f32 v235, v8, 0x3fb8aa3b, v194
	v_mov_b32_e32 v8, 0xff800000
	v_cndmask_b32_e64 v8, v8, v235, s[40:41]
	v_fmamk_f32 v235, v9, 0x3fb8aa3b, v195
	v_mov_b32_e32 v9, 0xff800000
	v_cndmask_b32_e64 v9, v9, v235, s[42:43]
	v_fmamk_f32 v235, v10, 0x3fb8aa3b, v196
	v_mov_b32_e32 v10, 0xff800000
	v_cndmask_b32_e64 v10, v10, v235, s[44:45]
	v_fmamk_f32 v235, v11, 0x3fb8aa3b, v197
	v_mov_b32_e32 v11, 0xff800000
	v_cndmask_b32_e64 v11, v11, v235, s[46:47]
	v_fmamk_f32 v235, v12, 0x3fb8aa3b, v198
	v_mov_b32_e32 v12, 0xff800000
	v_cndmask_b32_e64 v12, v12, v235, s[48:49]
	v_fmamk_f32 v235, v13, 0x3fb8aa3b, v199
	v_mov_b32_e32 v13, 0xff800000
	v_cndmask_b32_e64 v13, v13, v235, s[50:51]
	v_fmamk_f32 v235, v14, 0x3fb8aa3b, v200
	v_mov_b32_e32 v14, 0xff800000
	v_cndmask_b32_e64 v14, v14, v235, s[52:53]
	v_fmamk_f32 v235, v15, 0x3fb8aa3b, v201
	v_mov_b32_e32 v15, 0xff800000
	v_cndmask_b32_e64 v15, v15, v235, s[54:55]
	s_waitcnt vmcnt(63)
	v_mfma_f32_16x16x32_bf16 v[194:197], v[104:107], v[0:3], 0
	v_mfma_f32_16x16x32_bf16 v[198:201], v[112:115], v[0:3], 0
	v_mfma_f32_16x16x32_bf16 v[194:197], v[108:111], v[4:7], v[194:197]
	v_mfma_f32_16x16x32_bf16 v[198:201], v[116:119], v[4:7], v[198:201]
	s_waitcnt vmcnt(63)
	v_fmamk_f32 v235, v16, 0x3fb8aa3b, v202
	v_mov_b32_e32 v16, 0xff800000
	v_cndmask_b32_e64 v16, v16, v235, s[40:41]
	v_fmamk_f32 v235, v17, 0x3fb8aa3b, v203
	v_mov_b32_e32 v17, 0xff800000
	v_cndmask_b32_e64 v17, v17, v235, s[42:43]
	v_fmamk_f32 v235, v18, 0x3fb8aa3b, v204
	v_mov_b32_e32 v18, 0xff800000
	v_cndmask_b32_e64 v18, v18, v235, s[44:45]
	v_fmamk_f32 v235, v19, 0x3fb8aa3b, v205
	v_mov_b32_e32 v19, 0xff800000
	v_cndmask_b32_e64 v19, v19, v235, s[46:47]
	v_fmamk_f32 v235, v20, 0x3fb8aa3b, v206
	v_mov_b32_e32 v20, 0xff800000
	v_cndmask_b32_e64 v20, v20, v235, s[48:49]
	v_fmamk_f32 v235, v21, 0x3fb8aa3b, v207
	v_mov_b32_e32 v21, 0xff800000
	v_cndmask_b32_e64 v21, v21, v235, s[50:51]
	v_fmamk_f32 v235, v22, 0x3fb8aa3b, v208
	v_mov_b32_e32 v22, 0xff800000
	v_cndmask_b32_e64 v22, v22, v235, s[52:53]
	v_fmamk_f32 v235, v23, 0x3fb8aa3b, v209
	v_mov_b32_e32 v23, 0xff800000
	v_cndmask_b32_e64 v23, v23, v235, s[54:55]
	s_waitcnt vmcnt(63)
	v_mfma_f32_16x16x32_bf16 v[202:205], v[120:123], v[0:3], 0
	v_mfma_f32_16x16x32_bf16 v[206:209], v[128:131], v[0:3], 0
	v_mfma_f32_16x16x32_bf16 v[202:205], v[124:127], v[4:7], v[202:205]
	v_mfma_f32_16x16x32_bf16 v[206:209], v[132:135], v[4:7], v[206:209]
	s_waitcnt vmcnt(63)
	v_fmamk_f32 v235, v24, 0x3fb8aa3b, v194
	v_mov_b32_e32 v24, 0xff800000
	v_cndmask_b32_e64 v24, v24, v235, s[40:41]
	v_fmamk_f32 v235, v25, 0x3fb8aa3b, v195
	v_mov_b32_e32 v25, 0xff800000
	v_cndmask_b32_e64 v25, v25, v235, s[42:43]
	v_fmamk_f32 v235, v26, 0x3fb8aa3b, v196
	v_mov_b32_e32 v26, 0xff800000
	v_cndmask_b32_e64 v26, v26, v235, s[44:45]
	v_fmamk_f32 v235, v27, 0x3fb8aa3b, v197
	v_mov_b32_e32 v27, 0xff800000
	v_cndmask_b32_e64 v27, v27, v235, s[46:47]
	v_fmamk_f32 v235, v28, 0x3fb8aa3b, v198
	v_mov_b32_e32 v28, 0xff800000
	v_cndmask_b32_e64 v28, v28, v235, s[48:49]
	v_fmamk_f32 v235, v29, 0x3fb8aa3b, v199
	v_mov_b32_e32 v29, 0xff800000
	v_cndmask_b32_e64 v29, v29, v235, s[50:51]
	v_fmamk_f32 v235, v30, 0x3fb8aa3b, v200
	v_mov_b32_e32 v30, 0xff800000
	v_cndmask_b32_e64 v30, v30, v235, s[52:53]
	v_fmamk_f32 v235, v31, 0x3fb8aa3b, v201
	v_mov_b32_e32 v31, 0xff800000
	v_cndmask_b32_e64 v31, v31, v235, s[54:55]
	s_waitcnt vmcnt(63)
	v_mfma_f32_16x16x32_bf16 v[194:197], v[146:149], v[0:3], 0
	v_mfma_f32_16x16x32_bf16 v[198:201], v[154:157], v[0:3], 0
	v_mfma_f32_16x16x32_bf16 v[194:197], v[150:153], v[4:7], v[194:197]
	v_mfma_f32_16x16x32_bf16 v[198:201], v[158:161], v[4:7], v[198:201]
	s_waitcnt vmcnt(56)
	v_fmamk_f32 v235, v32, 0x3fb8aa3b, v202
	v_mov_b32_e32 v32, 0xff800000
	v_cndmask_b32_e64 v32, v32, v235, s[40:41]
	v_fmamk_f32 v235, v33, 0x3fb8aa3b, v203
	v_mov_b32_e32 v33, 0xff800000
	v_cndmask_b32_e64 v33, v33, v235, s[42:43]
	v_fmamk_f32 v235, v34, 0x3fb8aa3b, v204
	v_mov_b32_e32 v34, 0xff800000
	v_cndmask_b32_e64 v34, v34, v235, s[44:45]
	v_fmamk_f32 v235, v35, 0x3fb8aa3b, v205
	v_mov_b32_e32 v35, 0xff800000
	v_cndmask_b32_e64 v35, v35, v235, s[46:47]
	v_fmamk_f32 v235, v36, 0x3fb8aa3b, v206
	v_mov_b32_e32 v36, 0xff800000
	v_cndmask_b32_e64 v36, v36, v235, s[48:49]
	v_fmamk_f32 v235, v37, 0x3fb8aa3b, v207
	v_mov_b32_e32 v37, 0xff800000
	v_cndmask_b32_e64 v37, v37, v235, s[50:51]
	v_fmamk_f32 v235, v38, 0x3fb8aa3b, v208
	v_mov_b32_e32 v38, 0xff800000
	v_cndmask_b32_e64 v38, v38, v235, s[52:53]
	v_fmamk_f32 v235, v39, 0x3fb8aa3b, v209
	v_mov_b32_e32 v39, 0xff800000
	v_cndmask_b32_e64 v39, v39, v235, s[54:55]
	s_waitcnt vmcnt(63)
	v_mfma_f32_16x16x32_bf16 v[202:205], v[162:165], v[0:3], 0
	v_mfma_f32_16x16x32_bf16 v[206:209], v[170:173], v[0:3], 0
	v_mfma_f32_16x16x32_bf16 v[202:205], v[166:169], v[4:7], v[202:205]
	v_mfma_f32_16x16x32_bf16 v[206:209], v[174:177], v[4:7], v[206:209]
	s_waitcnt vmcnt(48)
	v_fmamk_f32 v235, v40, 0x3fb8aa3b, v194
	v_mov_b32_e32 v40, 0xff800000
	v_cndmask_b32_e64 v40, v40, v235, s[40:41]
	v_fmamk_f32 v235, v41, 0x3fb8aa3b, v195
	v_mov_b32_e32 v41, 0xff800000
	v_cndmask_b32_e64 v41, v41, v235, s[42:43]
	v_fmamk_f32 v235, v42, 0x3fb8aa3b, v196
	v_mov_b32_e32 v42, 0xff800000
	v_cndmask_b32_e64 v42, v42, v235, s[44:45]
	v_fmamk_f32 v235, v43, 0x3fb8aa3b, v197
	v_mov_b32_e32 v43, 0xff800000
	v_cndmask_b32_e64 v43, v43, v235, s[46:47]
	v_fmamk_f32 v235, v44, 0x3fb8aa3b, v198
	v_mov_b32_e32 v44, 0xff800000
	v_cndmask_b32_e64 v44, v44, v235, s[48:49]
	v_fmamk_f32 v235, v45, 0x3fb8aa3b, v199
	v_mov_b32_e32 v45, 0xff800000
	v_cndmask_b32_e64 v45, v45, v235, s[50:51]
	v_fmamk_f32 v235, v46, 0x3fb8aa3b, v200
	v_mov_b32_e32 v46, 0xff800000
	v_cndmask_b32_e64 v46, v46, v235, s[52:53]
	v_fmamk_f32 v235, v47, 0x3fb8aa3b, v201
	v_mov_b32_e32 v47, 0xff800000
	v_cndmask_b32_e64 v47, v47, v235, s[54:55]
	s_waitcnt vmcnt(4)
	v_mfma_f32_16x16x32_bf16 v[194:197], v[72:75], v[0:3], 0
	v_mfma_f32_16x16x32_bf16 v[198:201], v[80:83], v[0:3], 0
	v_mfma_f32_16x16x32_bf16 v[194:197], v[76:79], v[4:7], v[194:197]
	v_mfma_f32_16x16x32_bf16 v[198:201], v[84:87], v[4:7], v[198:201]
	s_waitcnt vmcnt(40)
	v_fmamk_f32 v235, v48, 0x3fb8aa3b, v202
	v_mov_b32_e32 v48, 0xff800000
	v_cndmask_b32_e64 v48, v48, v235, s[40:41]
	v_fmamk_f32 v235, v49, 0x3fb8aa3b, v203
	v_mov_b32_e32 v49, 0xff800000
	v_cndmask_b32_e64 v49, v49, v235, s[42:43]
	v_fmamk_f32 v235, v50, 0x3fb8aa3b, v204
	v_mov_b32_e32 v50, 0xff800000
	v_cndmask_b32_e64 v50, v50, v235, s[44:45]
	v_fmamk_f32 v235, v51, 0x3fb8aa3b, v205
	v_mov_b32_e32 v51, 0xff800000
	v_cndmask_b32_e64 v51, v51, v235, s[46:47]
	v_fmamk_f32 v235, v52, 0x3fb8aa3b, v206
	v_mov_b32_e32 v52, 0xff800000
	v_cndmask_b32_e64 v52, v52, v235, s[48:49]
	v_fmamk_f32 v235, v53, 0x3fb8aa3b, v207
	v_mov_b32_e32 v53, 0xff800000
	v_cndmask_b32_e64 v53, v53, v235, s[50:51]
	v_fmamk_f32 v235, v54, 0x3fb8aa3b, v208
	v_mov_b32_e32 v54, 0xff800000
	v_cndmask_b32_e64 v54, v54, v235, s[52:53]
	v_fmamk_f32 v235, v55, 0x3fb8aa3b, v209
	v_mov_b32_e32 v55, 0xff800000
	v_cndmask_b32_e64 v55, v55, v235, s[54:55]
	s_waitcnt vmcnt(0)
	v_mfma_f32_16x16x32_bf16 v[202:205], v[88:91], v[0:3], 0
	v_mfma_f32_16x16x32_bf16 v[206:209], v[96:99], v[0:3], 0
	v_mfma_f32_16x16x32_bf16 v[202:205], v[92:95], v[4:7], v[202:205]
	v_mfma_f32_16x16x32_bf16 v[206:209], v[100:103], v[4:7], v[206:209]
	s_waitcnt vmcnt(32)
	v_fmamk_f32 v235, v56, 0x3fb8aa3b, v194
	v_mov_b32_e32 v56, 0xff800000
	v_cndmask_b32_e64 v56, v56, v235, s[40:41]
	v_fmamk_f32 v235, v57, 0x3fb8aa3b, v195
	v_mov_b32_e32 v57, 0xff800000
	v_cndmask_b32_e64 v57, v57, v235, s[42:43]
	v_fmamk_f32 v235, v58, 0x3fb8aa3b, v196
	v_mov_b32_e32 v58, 0xff800000
	v_cndmask_b32_e64 v58, v58, v235, s[44:45]
	v_fmamk_f32 v235, v59, 0x3fb8aa3b, v197
	v_mov_b32_e32 v59, 0xff800000
	v_cndmask_b32_e64 v59, v59, v235, s[46:47]
	v_fmamk_f32 v235, v60, 0x3fb8aa3b, v198
	v_mov_b32_e32 v60, 0xff800000
	v_cndmask_b32_e64 v60, v60, v235, s[48:49]
	v_fmamk_f32 v235, v61, 0x3fb8aa3b, v199
	v_mov_b32_e32 v61, 0xff800000
	v_cndmask_b32_e64 v61, v61, v235, s[50:51]
	v_fmamk_f32 v235, v62, 0x3fb8aa3b, v200
	v_mov_b32_e32 v62, 0xff800000
	v_cndmask_b32_e64 v62, v62, v235, s[52:53]
	v_fmamk_f32 v235, v63, 0x3fb8aa3b, v201
	v_mov_b32_e32 v63, 0xff800000
	v_cndmask_b32_e64 v63, v63, v235, s[54:55]
	s_nop 7
	s_waitcnt vmcnt(24)
	v_fmamk_f32 v235, v64, 0x3fb8aa3b, v202
	v_mov_b32_e32 v64, 0xff800000
	v_cndmask_b32_e64 v64, v64, v235, s[40:41]
	v_fmamk_f32 v235, v65, 0x3fb8aa3b, v203
	v_mov_b32_e32 v65, 0xff800000
	v_cndmask_b32_e64 v65, v65, v235, s[42:43]
	v_fmamk_f32 v235, v66, 0x3fb8aa3b, v204
	v_mov_b32_e32 v66, 0xff800000
	v_cndmask_b32_e64 v66, v66, v235, s[44:45]
	v_fmamk_f32 v235, v67, 0x3fb8aa3b, v205
	v_mov_b32_e32 v67, 0xff800000
	v_cndmask_b32_e64 v67, v67, v235, s[46:47]
	v_fmamk_f32 v235, v68, 0x3fb8aa3b, v206
	v_mov_b32_e32 v68, 0xff800000
	v_cndmask_b32_e64 v68, v68, v235, s[48:49]
	v_fmamk_f32 v235, v69, 0x3fb8aa3b, v207
	v_mov_b32_e32 v69, 0xff800000
	v_cndmask_b32_e64 v69, v69, v235, s[50:51]
	v_fmamk_f32 v235, v70, 0x3fb8aa3b, v208
	v_mov_b32_e32 v70, 0xff800000
	v_cndmask_b32_e64 v70, v70, v235, s[52:53]
	v_fmamk_f32 v235, v71, 0x3fb8aa3b, v209
	v_mov_b32_e32 v71, 0xff800000
	v_cndmask_b32_e64 v71, v71, v235, s[54:55]
	s_bfe_u32 s36, s98, 0x80008
	s_sub_u32 s36, s36, 1
	s_cmp_lt_u32 s14, s36
	s_cbranch_scc0 .Lna_nopf
	s_add_u32 s7, s7, 0x200
	s_and_b32 s15, s7, 7
	s_bfe_u32 s16, s7, 0x50003
	s_lshr_b32 s17, s7, 8
	s_sub_i32 s18, s16, 4
	s_max_i32 s18, s18, 0
	s_min_i32 s18, s18, 24
	s_lshl_b32 s19, s17, 11
	s_lshl_b32 s20, s18, 6
	s_add_u32 s20, s20, s19
	s_add_u32 s20, s20, s8
	s_lshl_b32 s21, s16, 6
	s_add_u32 s21, s21, s19
	s_add_u32 s21, s21, s9
	s_lshl_b32 s22, s15, 7
	s_lshl_b32 s23, s20, 10
	s_add_u32 s23, s23, s22
	s_add_u32 s0, s10, 0x5200000
	s_addc_u32 s1, s11, 0
	s_add_u32 s0, s0, s23
	s_addc_u32 s1, s1, 0
	s_lshl_b32 s23, s21, 10
	s_add_u32 s23, s23, s22
	s_add_u32 s2, s10, 0x4200000
	s_addc_u32 s3, s11, 0
	s_add_u32 s2, s2, s23
	s_addc_u32 s3, s3, 0
	global_load_dwordx4 v[0:3], v221, s[2:3]
	global_load_dwordx4 v[4:7], v221, s[2:3] offset:64
	global_load_dwordx4 v[72:75], v218, s[0:1]
	global_load_dwordx4 v[76:79], v218, s[0:1] offset:64
	global_load_dwordx4 v[80:83], v219, s[0:1]
	global_load_dwordx4 v[84:87], v219, s[0:1] offset:64
	s_add_u32 s0, s0, 0x10000
	s_addc_u32 s1, s1, 0
	global_load_dwordx4 v[88:91], v218, s[0:1]
	global_load_dwordx4 v[92:95], v218, s[0:1] offset:64
	global_load_dwordx4 v[96:99], v219, s[0:1]
	global_load_dwordx4 v[100:103], v219, s[0:1] offset:64
	s_add_u32 s0, s0, 0x10000
	s_addc_u32 s1, s1, 0
	global_load_dwordx4 v[104:107], v218, s[0:1]
	global_load_dwordx4 v[108:111], v218, s[0:1] offset:64
	global_load_dwordx4 v[112:115], v219, s[0:1]
	global_load_dwordx4 v[116:119], v219, s[0:1] offset:64
	s_add_u32 s0, s0, 0x10000
	s_addc_u32 s1, s1, 0
	global_load_dwordx4 v[120:123], v218, s[0:1]
	global_load_dwordx4 v[124:127], v218, s[0:1] offset:64
	global_load_dwordx4 v[128:131], v219, s[0:1]
	global_load_dwordx4 v[132:135], v219, s[0:1] offset:64
	s_add_u32 s0, s0, 0x10000
	s_addc_u32 s1, s1, 0
	global_load_dwordx4 v[146:149], v218, s[0:1]
	global_load_dwordx4 v[150:153], v218, s[0:1] offset:64
	global_load_dwordx4 v[154:157], v219, s[0:1]
	global_load_dwordx4 v[158:161], v219, s[0:1] offset:64
	s_add_u32 s0, s0, 0x10000
	s_addc_u32 s1, s1, 0
	global_load_dwordx4 v[162:165], v218, s[0:1]
	global_load_dwordx4 v[166:169], v218, s[0:1] offset:64
	global_load_dwordx4 v[170:173], v219, s[0:1]
	global_load_dwordx4 v[174:177], v219, s[0:1] offset:64
	s_add_u32 s0, s0, 0x10000
	s_addc_u32 s1, s1, 0
.Lna_nopf:
	v_max3_f32 v233, v8, v9, v10
	v_max_f32_e32 v233, v233, v11
	v_max_f32_e32 v233, v233, v12
	v_max_f32_e32 v233, v233, v13
	v_max_f32_e32 v233, v233, v14
	v_max_f32_e32 v233, v233, v15
	v_max_f32_e32 v233, v233, v16
	v_max_f32_e32 v233, v233, v17
	v_max_f32_e32 v233, v233, v18
	v_max_f32_e32 v233, v233, v19
	v_max_f32_e32 v233, v233, v20
	v_max_f32_e32 v233, v233, v21
	v_max_f32_e32 v233, v233, v22
	v_max_f32_e32 v233, v233, v23
	v_max_f32_e32 v233, v233, v24
	v_max_f32_e32 v233, v233, v25
	v_max_f32_e32 v233, v233, v26
	v_max_f32_e32 v233, v233, v27
	v_max_f32_e32 v233, v233, v28
	v_max_f32_e32 v233, v233, v29
	v_max_f32_e32 v233, v233, v30
	v_max_f32_e32 v233, v233, v31
	v_max_f32_e32 v233, v233, v32
	v_max_f32_e32 v233, v233, v33
	v_max_f32_e32 v233, v233, v34
	v_max_f32_e32 v233, v233, v35
	v_max_f32_e32 v233, v233, v36
	v_max_f32_e32 v233, v233, v37
	v_max_f32_e32 v233, v233, v38
	v_max_f32_e32 v233, v233, v39
	v_max_f32_e32 v233, v233, v40
	v_max_f32_e32 v233, v233, v41
	v_max_f32_e32 v233, v233, v42
	v_max_f32_e32 v233, v233, v43
	v_max_f32_e32 v233, v233, v44
	v_max_f32_e32 v233, v233, v45
	v_max_f32_e32 v233, v233, v46
	v_max_f32_e32 v233, v233, v47
	v_max_f32_e32 v233, v233, v48
	v_max_f32_e32 v233, v233, v49
	v_max_f32_e32 v233, v233, v50
	v_max_f32_e32 v233, v233, v51
	v_max_f32_e32 v233, v233, v52
	v_max_f32_e32 v233, v233, v53
	v_max_f32_e32 v233, v233, v54
	v_max_f32_e32 v233, v233, v55
	v_max_f32_e32 v233, v233, v56
	v_max_f32_e32 v233, v233, v57
	v_max_f32_e32 v233, v233, v58
	v_max_f32_e32 v233, v233, v59
	v_max_f32_e32 v233, v233, v60
	v_max_f32_e32 v233, v233, v61
	v_max_f32_e32 v233, v233, v62
	v_max_f32_e32 v233, v233, v63
	v_max_f32_e32 v233, v233, v64
	v_max_f32_e32 v233, v233, v65
	v_max_f32_e32 v233, v233, v66
	v_max_f32_e32 v233, v233, v67
	v_max_f32_e32 v233, v233, v68
	v_max_f32_e32 v233, v233, v69
	v_max_f32_e32 v233, v233, v70
	v_max_f32_e32 v233, v233, v71
	ds_bpermute_b32 v235, v223, v233
	s_waitcnt lgkmcnt(0)
	v_max_f32_e32 v233, v233, v235
	ds_bpermute_b32 v235, v232, v233
	s_waitcnt lgkmcnt(0)
	v_max_f32_e32 v233, v233, v235
	v_mov_b32_e32 v234, 0
	v_sub_f32_e32 v8, v8, v233
	v_exp_f32_e32 v8, v8
	v_sub_f32_e32 v9, v9, v233
	v_add_f32_e32 v234, v234, v8
	v_exp_f32_e32 v9, v9
	v_sub_f32_e32 v10, v10, v233
	v_add_f32_e32 v234, v234, v9
	v_exp_f32_e32 v10, v10
	v_sub_f32_e32 v11, v11, v233
	v_add_f32_e32 v234, v234, v10
	v_exp_f32_e32 v11, v11
	v_sub_f32_e32 v12, v12, v233
	v_add_f32_e32 v234, v234, v11
	v_exp_f32_e32 v12, v12
	v_sub_f32_e32 v13, v13, v233
	v_add_f32_e32 v234, v234, v12
	v_exp_f32_e32 v13, v13
	v_sub_f32_e32 v14, v14, v233
	v_add_f32_e32 v234, v234, v13
	v_exp_f32_e32 v14, v14
	v_sub_f32_e32 v15, v15, v233
	v_add_f32_e32 v234, v234, v14
	v_exp_f32_e32 v15, v15
	v_sub_f32_e32 v16, v16, v233
	v_add_f32_e32 v234, v234, v15
	v_exp_f32_e32 v16, v16
	v_sub_f32_e32 v17, v17, v233
	v_add_f32_e32 v234, v234, v16
	v_exp_f32_e32 v17, v17
	v_sub_f32_e32 v18, v18, v233
	v_add_f32_e32 v234, v234, v17
	v_exp_f32_e32 v18, v18
	v_sub_f32_e32 v19, v19, v233
	v_add_f32_e32 v234, v234, v18
	v_exp_f32_e32 v19, v19
	v_sub_f32_e32 v20, v20, v233
	v_add_f32_e32 v234, v234, v19
	v_exp_f32_e32 v20, v20
	v_sub_f32_e32 v21, v21, v233
	v_add_f32_e32 v234, v234, v20
	v_exp_f32_e32 v21, v21
	v_sub_f32_e32 v22, v22, v233
	v_add_f32_e32 v234, v234, v21
	v_exp_f32_e32 v22, v22
	v_sub_f32_e32 v23, v23, v233
	v_add_f32_e32 v234, v234, v22
	v_exp_f32_e32 v23, v23
	v_sub_f32_e32 v24, v24, v233
	v_add_f32_e32 v234, v234, v23
	v_exp_f32_e32 v24, v24
	v_sub_f32_e32 v25, v25, v233
	v_add_f32_e32 v234, v234, v24
	v_exp_f32_e32 v25, v25
	v_sub_f32_e32 v26, v26, v233
	v_add_f32_e32 v234, v234, v25
	v_exp_f32_e32 v26, v26
	v_sub_f32_e32 v27, v27, v233
	v_add_f32_e32 v234, v234, v26
	v_exp_f32_e32 v27, v27
	v_sub_f32_e32 v28, v28, v233
	v_add_f32_e32 v234, v234, v27
	v_exp_f32_e32 v28, v28
	v_sub_f32_e32 v29, v29, v233
	v_add_f32_e32 v234, v234, v28
	v_exp_f32_e32 v29, v29
	v_sub_f32_e32 v30, v30, v233
	v_add_f32_e32 v234, v234, v29
	v_exp_f32_e32 v30, v30
	v_sub_f32_e32 v31, v31, v233
	v_add_f32_e32 v234, v234, v30
	v_exp_f32_e32 v31, v31
	v_sub_f32_e32 v32, v32, v233
	v_add_f32_e32 v234, v234, v31
	v_exp_f32_e32 v32, v32
	v_sub_f32_e32 v33, v33, v233
	v_add_f32_e32 v234, v234, v32
	v_exp_f32_e32 v33, v33
	v_sub_f32_e32 v34, v34, v233
	v_add_f32_e32 v234, v234, v33
	v_exp_f32_e32 v34, v34
	v_sub_f32_e32 v35, v35, v233
	v_add_f32_e32 v234, v234, v34
	v_exp_f32_e32 v35, v35
	v_sub_f32_e32 v36, v36, v233
	v_add_f32_e32 v234, v234, v35
	v_exp_f32_e32 v36, v36
	v_sub_f32_e32 v37, v37, v233
	v_add_f32_e32 v234, v234, v36
	v_exp_f32_e32 v37, v37
	v_sub_f32_e32 v38, v38, v233
	v_add_f32_e32 v234, v234, v37
	v_exp_f32_e32 v38, v38
	v_sub_f32_e32 v39, v39, v233
	v_add_f32_e32 v234, v234, v38
	v_exp_f32_e32 v39, v39
	v_sub_f32_e32 v40, v40, v233
	v_add_f32_e32 v234, v234, v39
	v_exp_f32_e32 v40, v40
	v_sub_f32_e32 v41, v41, v233
	v_add_f32_e32 v234, v234, v40
	v_exp_f32_e32 v41, v41
	v_sub_f32_e32 v42, v42, v233
	v_add_f32_e32 v234, v234, v41
	v_exp_f32_e32 v42, v42
	v_sub_f32_e32 v43, v43, v233
	v_add_f32_e32 v234, v234, v42
	v_exp_f32_e32 v43, v43
	v_sub_f32_e32 v44, v44, v233
	v_add_f32_e32 v234, v234, v43
	v_exp_f32_e32 v44, v44
	v_sub_f32_e32 v45, v45, v233
	v_add_f32_e32 v234, v234, v44
	v_exp_f32_e32 v45, v45
	v_sub_f32_e32 v46, v46, v233
	v_add_f32_e32 v234, v234, v45
	v_exp_f32_e32 v46, v46
	v_sub_f32_e32 v47, v47, v233
	v_add_f32_e32 v234, v234, v46
	v_exp_f32_e32 v47, v47
	v_sub_f32_e32 v48, v48, v233
	v_add_f32_e32 v234, v234, v47
	v_exp_f32_e32 v48, v48
	v_sub_f32_e32 v49, v49, v233
	v_add_f32_e32 v234, v234, v48
	v_exp_f32_e32 v49, v49
	v_sub_f32_e32 v50, v50, v233
	v_add_f32_e32 v234, v234, v49
	v_exp_f32_e32 v50, v50
	v_sub_f32_e32 v51, v51, v233
	v_add_f32_e32 v234, v234, v50
	v_exp_f32_e32 v51, v51
	v_sub_f32_e32 v52, v52, v233
	v_add_f32_e32 v234, v234, v51
	v_exp_f32_e32 v52, v52
	v_sub_f32_e32 v53, v53, v233
	v_add_f32_e32 v234, v234, v52
	v_exp_f32_e32 v53, v53
	v_sub_f32_e32 v54, v54, v233
	v_add_f32_e32 v234, v234, v53
	v_exp_f32_e32 v54, v54
	v_sub_f32_e32 v55, v55, v233
	v_add_f32_e32 v234, v234, v54
	v_exp_f32_e32 v55, v55
	v_sub_f32_e32 v56, v56, v233
	v_add_f32_e32 v234, v234, v55
	v_exp_f32_e32 v56, v56
	v_sub_f32_e32 v57, v57, v233
	v_add_f32_e32 v234, v234, v56
	v_exp_f32_e32 v57, v57
	v_sub_f32_e32 v58, v58, v233
	v_add_f32_e32 v234, v234, v57
	v_exp_f32_e32 v58, v58
	v_sub_f32_e32 v59, v59, v233
	v_add_f32_e32 v234, v234, v58
	v_exp_f32_e32 v59, v59
	v_sub_f32_e32 v60, v60, v233
	v_add_f32_e32 v234, v234, v59
	v_exp_f32_e32 v60, v60
	v_sub_f32_e32 v61, v61, v233
	v_add_f32_e32 v234, v234, v60
	v_exp_f32_e32 v61, v61
	v_sub_f32_e32 v62, v62, v233
	v_add_f32_e32 v234, v234, v61
	v_exp_f32_e32 v62, v62
	v_sub_f32_e32 v63, v63, v233
	v_add_f32_e32 v234, v234, v62
	v_exp_f32_e32 v63, v63
	v_sub_f32_e32 v64, v64, v233
	v_add_f32_e32 v234, v234, v63
	v_exp_f32_e32 v64, v64
	v_sub_f32_e32 v65, v65, v233
	v_add_f32_e32 v234, v234, v64
	v_exp_f32_e32 v65, v65
	v_sub_f32_e32 v66, v66, v233
	v_add_f32_e32 v234, v234, v65
	v_exp_f32_e32 v66, v66
	v_sub_f32_e32 v67, v67, v233
	v_add_f32_e32 v234, v234, v66
	v_exp_f32_e32 v67, v67
	v_sub_f32_e32 v68, v68, v233
	v_add_f32_e32 v234, v234, v67
	v_exp_f32_e32 v68, v68
	v_sub_f32_e32 v69, v69, v233
	v_add_f32_e32 v234, v234, v68
	v_exp_f32_e32 v69, v69
	v_sub_f32_e32 v70, v70, v233
	v_add_f32_e32 v234, v234, v69
	v_exp_f32_e32 v70, v70
	v_sub_f32_e32 v71, v71, v233
	v_add_f32_e32 v234, v234, v70
	v_exp_f32_e32 v71, v71
	s_nop 0
	v_add_f32_e32 v234, v234, v71
	ds_bpermute_b32 v235, v223, v234
	v_cvt_pk_bf16_f32 v8, v8, v9
	v_cvt_pk_bf16_f32 v9, v10, v11
	v_cvt_pk_bf16_f32 v10, v12, v13
	v_cvt_pk_bf16_f32 v11, v14, v15
	v_cvt_pk_bf16_f32 v16, v16, v17
	v_cvt_pk_bf16_f32 v17, v18, v19
	v_cvt_pk_bf16_f32 v18, v20, v21
	v_cvt_pk_bf16_f32 v19, v22, v23
	v_cvt_pk_bf16_f32 v24, v24, v25
	v_cvt_pk_bf16_f32 v25, v26, v27
	v_cvt_pk_bf16_f32 v26, v28, v29
	v_cvt_pk_bf16_f32 v27, v30, v31
	v_cvt_pk_bf16_f32 v32, v32, v33
	v_cvt_pk_bf16_f32 v33, v34, v35
	v_cvt_pk_bf16_f32 v34, v36, v37
	v_cvt_pk_bf16_f32 v35, v38, v39
	v_cvt_pk_bf16_f32 v40, v40, v41
	v_cvt_pk_bf16_f32 v41, v42, v43
	v_cvt_pk_bf16_f32 v42, v44, v45
	v_cvt_pk_bf16_f32 v43, v46, v47
	v_cvt_pk_bf16_f32 v48, v48, v49
	v_cvt_pk_bf16_f32 v49, v50, v51
	v_cvt_pk_bf16_f32 v50, v52, v53
	v_cvt_pk_bf16_f32 v51, v54, v55
	v_cvt_pk_bf16_f32 v56, v56, v57
	v_cvt_pk_bf16_f32 v57, v58, v59
	v_cvt_pk_bf16_f32 v58, v60, v61
	v_cvt_pk_bf16_f32 v59, v62, v63
	v_cvt_pk_bf16_f32 v64, v64, v65
	v_cvt_pk_bf16_f32 v65, v66, v67
	v_cvt_pk_bf16_f32 v66, v68, v69
	v_cvt_pk_bf16_f32 v67, v70, v71
	s_waitcnt lgkmcnt(0)
	v_add_f32_e32 v234, v234, v235
	ds_bpermute_b32 v235, v232, v234
	s_waitcnt lgkmcnt(0)
	v_add_f32_e32 v234, v234, v235
	s_barrier
	v_mov_b32_e32 v138, v136
	ds_read_b128 v[12:15], v138 offset:16
	ds_read_b128 v[20:23], v138 offset:16400
	ds_read_b128 v[28:31], v138 offset:32784
	ds_read_b128 v[36:39], v138 offset:49168
	v_xor_b32_e32 v138, 128, v136
	ds_read_b128 v[44:47], v138 offset:16
	ds_read_b128 v[52:55], v138 offset:16400
	ds_read_b128 v[60:63], v138 offset:32784
	ds_read_b128 v[68:71], v138 offset:49168
	v_xor_b32_e32 v138, 256, v136
	ds_read_b128 v[194:197], v138 offset:16
	ds_read_b128 v[198:201], v138 offset:16400
	ds_read_b128 v[202:205], v138 offset:32784
	ds_read_b128 v[206:209], v138 offset:49168
	s_waitcnt lgkmcnt(8)
	v_mfma_f32_16x16x32_bf16 v[178:181], v[12:15], v[8:11], v[178:181]
	v_mfma_f32_16x16x32_bf16 v[182:185], v[20:23], v[8:11], v[182:185]
	v_mfma_f32_16x16x32_bf16 v[186:189], v[28:31], v[8:11], v[186:189]
	v_mfma_f32_16x16x32_bf16 v[190:193], v[36:39], v[8:11], v[190:193]
	v_xor_b32_e32 v138, 384, v136
	ds_read_b128 v[12:15], v138 offset:16
	ds_read_b128 v[20:23], v138 offset:16400
	ds_read_b128 v[28:31], v138 offset:32784
	ds_read_b128 v[36:39], v138 offset:49168
	s_waitcnt lgkmcnt(8)
	v_mfma_f32_16x16x32_bf16 v[178:181], v[44:47], v[16:19], v[178:181]
	v_mfma_f32_16x16x32_bf16 v[182:185], v[52:55], v[16:19], v[182:185]
	v_mfma_f32_16x16x32_bf16 v[186:189], v[60:63], v[16:19], v[186:189]
	v_mfma_f32_16x16x32_bf16 v[190:193], v[68:71], v[16:19], v[190:193]
	v_xor_b32_e32 v138, 512, v136
	ds_read_b128 v[44:47], v138 offset:16
	ds_read_b128 v[52:55], v138 offset:16400
	ds_read_b128 v[60:63], v138 offset:32784
	ds_read_b128 v[68:71], v138 offset:49168
	s_waitcnt lgkmcnt(8)
	v_mfma_f32_16x16x32_bf16 v[178:181], v[194:197], v[24:27], v[178:181]
	v_mfma_f32_16x16x32_bf16 v[182:185], v[198:201], v[24:27], v[182:185]
	v_mfma_f32_16x16x32_bf16 v[186:189], v[202:205], v[24:27], v[186:189]
	v_mfma_f32_16x16x32_bf16 v[190:193], v[206:209], v[24:27], v[190:193]
	v_xor_b32_e32 v138, 640, v136
	ds_read_b128 v[194:197], v138 offset:16
	ds_read_b128 v[198:201], v138 offset:16400
	ds_read_b128 v[202:205], v138 offset:32784
	ds_read_b128 v[206:209], v138 offset:49168
	s_waitcnt lgkmcnt(8)
	v_mfma_f32_16x16x32_bf16 v[178:181], v[12:15], v[32:35], v[178:181]
	v_mfma_f32_16x16x32_bf16 v[182:185], v[20:23], v[32:35], v[182:185]
	v_mfma_f32_16x16x32_bf16 v[186:189], v[28:31], v[32:35], v[186:189]
	v_mfma_f32_16x16x32_bf16 v[190:193], v[36:39], v[32:35], v[190:193]
	v_xor_b32_e32 v138, 768, v136
	ds_read_b128 v[12:15], v138 offset:16
	ds_read_b128 v[20:23], v138 offset:16400
	ds_read_b128 v[28:31], v138 offset:32784
	ds_read_b128 v[36:39], v138 offset:49168
	s_waitcnt lgkmcnt(8)
	v_mfma_f32_16x16x32_bf16 v[178:181], v[44:47], v[40:43], v[178:181]
	v_mfma_f32_16x16x32_bf16 v[182:185], v[52:55], v[40:43], v[182:185]
	v_mfma_f32_16x16x32_bf16 v[186:189], v[60:63], v[40:43], v[186:189]
	v_mfma_f32_16x16x32_bf16 v[190:193], v[68:71], v[40:43], v[190:193]
	v_xor_b32_e32 v138, 896, v136
	ds_read_b128 v[44:47], v138 offset:16
	ds_read_b128 v[52:55], v138 offset:16400
	ds_read_b128 v[60:63], v138 offset:32784
	ds_read_b128 v[68:71], v138 offset:49168
	s_waitcnt lgkmcnt(8)
	v_mfma_f32_16x16x32_bf16 v[178:181], v[194:197], v[48:51], v[178:181]
	v_mfma_f32_16x16x32_bf16 v[182:185], v[198:201], v[48:51], v[182:185]
	v_mfma_f32_16x16x32_bf16 v[186:189], v[202:205], v[48:51], v[186:189]
	v_mfma_f32_16x16x32_bf16 v[190:193], v[206:209], v[48:51], v[190:193]
	s_waitcnt lgkmcnt(4)
	v_mfma_f32_16x16x32_bf16 v[178:181], v[12:15], v[56:59], v[178:181]
	v_mfma_f32_16x16x32_bf16 v[182:185], v[20:23], v[56:59], v[182:185]
	v_mfma_f32_16x16x32_bf16 v[186:189], v[28:31], v[56:59], v[186:189]
	v_mfma_f32_16x16x32_bf16 v[190:193], v[36:39], v[56:59], v[190:193]
	s_waitcnt lgkmcnt(0)
	v_mfma_f32_16x16x32_bf16 v[178:181], v[44:47], v[64:67], v[178:181]
	v_mfma_f32_16x16x32_bf16 v[182:185], v[52:55], v[64:67], v[182:185]
	v_mfma_f32_16x16x32_bf16 v[186:189], v[60:63], v[64:67], v[186:189]
	v_mfma_f32_16x16x32_bf16 v[190:193], v[68:71], v[64:67], v[190:193]
	v_div_scale_f32 v235, s[36:37], v234, v234, 1.0
	v_rcp_f32_e32 v236, v235
	s_nop 0
	v_fma_f32 v237, -v235, v236, 1.0
	v_fmac_f32_e32 v236, v237, v236
	v_div_scale_f32 v237, vcc, 1.0, v234, 1.0
	v_mul_f32_e32 v240, v237, v236
	v_fma_f32 v241, -v235, v240, v237
	v_fmac_f32_e32 v240, v241, v236
	v_fma_f32 v235, -v235, v240, v237
	v_div_fmas_f32 v235, v235, v236, v240
	v_div_fixup_f32 v233, v235, v234, 1.0
	s_nop 3
	v_mul_f32_e32 v178, v178, v233
	v_mul_f32_e32 v179, v179, v233
	v_mul_f32_e32 v180, v180, v233
	v_mul_f32_e32 v181, v181, v233
	v_cvt_pk_bf16_f32 v178, v178, v179
	v_cvt_pk_bf16_f32 v179, v180, v181
	global_store_dwordx2 v222, v[178:179], s[32:33]
	v_mul_f32_e32 v182, v182, v233
	v_mul_f32_e32 v183, v183, v233
	v_mul_f32_e32 v184, v184, v233
	v_mul_f32_e32 v185, v185, v233
	v_cvt_pk_bf16_f32 v182, v182, v183
	v_cvt_pk_bf16_f32 v183, v184, v185
	global_store_dwordx2 v222, v[182:183], s[32:33] offset:32
	v_mul_f32_e32 v186, v186, v233
	v_mul_f32_e32 v187, v187, v233
	v_mul_f32_e32 v188, v188, v233
	v_mul_f32_e32 v189, v189, v233
	v_cvt_pk_bf16_f32 v186, v186, v187
	v_cvt_pk_bf16_f32 v187, v188, v189
	global_store_dwordx2 v222, v[186:187], s[32:33] offset:64
	v_mul_f32_e32 v190, v190, v233
	v_mul_f32_e32 v191, v191, v233
	v_mul_f32_e32 v192, v192, v233
	v_mul_f32_e32 v193, v193, v233
	v_cvt_pk_bf16_f32 v190, v190, v191
	v_cvt_pk_bf16_f32 v191, v192, v193
	global_store_dwordx2 v222, v[190:191], s[32:33] offset:96
	s_add_u32 s14, s14, 1
	s_bfe_u32 s36, s98, 0x80008
	s_cmp_lt_u32 s14, s36
	s_cbranch_scc1 .Lna_tile
	v_readlane_b32 s0, v245, 0
	v_readlane_b32 s1, v245, 1
	v_readlane_b32 s2, v245, 2
	v_readlane_b32 s3, v245, 3
	v_readlane_b32 s4, v245, 4
	v_readlane_b32 s5, v245, 5
	v_readlane_b32 s6, v245, 6
	v_readlane_b32 s7, v245, 7
	v_readlane_b32 s8, v245, 8
	v_readlane_b32 s9, v245, 9
	v_readlane_b32 s10, v245, 10
	v_readlane_b32 s11, v245, 11
	v_readlane_b32 s12, v245, 12
	v_readlane_b32 s13, v245, 13
	v_readlane_b32 s14, v245, 14
	v_readlane_b32 s15, v245, 15
	v_readlane_b32 s16, v245, 16
	v_readlane_b32 s17, v245, 17
	v_readlane_b32 s18, v245, 18
	v_readlane_b32 s19, v245, 19
	v_readlane_b32 s20, v245, 20
	v_readlane_b32 s21, v245, 21
	v_readlane_b32 s22, v245, 22
	v_readlane_b32 s23, v245, 23
	v_readlane_b32 s24, v245, 24
	v_readlane_b32 s25, v245, 25
	v_readlane_b32 s26, v245, 26
	v_readlane_b32 s27, v245, 27
	v_readlane_b32 s28, v245, 28
	v_readlane_b32 s29, v245, 29
	v_readlane_b32 s30, v245, 30
	v_readlane_b32 s31, v245, 31
	v_readlane_b32 s32, v245, 32
	v_readlane_b32 s33, v245, 33
	v_readlane_b32 s34, v245, 34
	v_readlane_b32 s35, v245, 35
	v_readlane_b32 s36, v245, 36
	v_readlane_b32 s37, v245, 37
	v_readlane_b32 s38, v245, 38
	v_readlane_b32 s39, v245, 39
	v_readlane_b32 s40, v245, 40
	v_readlane_b32 s41, v245, 41
	v_readlane_b32 s42, v245, 42
	v_readlane_b32 s43, v245, 43
	v_readlane_b32 s44, v245, 44
	v_readlane_b32 s45, v245, 45
	v_readlane_b32 s46, v245, 46
	v_readlane_b32 s47, v245, 47
	v_readlane_b32 s48, v245, 48
	v_readlane_b32 s49, v245, 49
	v_readlane_b32 s50, v245, 50
	v_readlane_b32 s51, v245, 51
	v_readlane_b32 s52, v245, 52
	v_readlane_b32 s53, v245, 53
	v_readlane_b32 s54, v245, 54
	v_readlane_b32 s55, v245, 55
	v_readlane_b32 s56, v245, 56
	v_readlane_b32 s57, v245, 57
	v_readlane_b32 s58, v245, 58
	v_readlane_b32 s59, v245, 59
	v_readlane_b32 s60, v245, 60
	v_readlane_b32 s61, v245, 61
	v_readlane_b32 s62, v245, 62
	v_readlane_b32 s63, v245, 63
	v_readlane_b32 s64, v244, 0
	v_readlane_b32 s65, v244, 1
	v_readlane_b32 s66, v244, 2
	v_readlane_b32 s67, v244, 3
	v_readlane_b32 s68, v244, 4
	v_readlane_b32 s69, v244, 5
	v_readlane_b32 s70, v244, 6
	v_readlane_b32 s71, v244, 7
	v_readlane_b32 s72, v244, 8
	v_readlane_b32 s73, v244, 9
	v_readlane_b32 s74, v244, 10
	v_readlane_b32 s75, v244, 11
	v_readlane_b32 s76, v244, 12
	v_readlane_b32 s77, v244, 13
	v_readlane_b32 s78, v244, 14
	v_readlane_b32 s79, v244, 15
	s_bitcmp1_b32 s98, 16
	s_cbranch_scc1 .LBB0_1107

.Lcv_nn7:
	s_add_u32 s6, s6, 0x200
	s_cmp_lt_u32 s6, 0x400
	s_cbranch_scc1 .Lcv_tile
	v_readlane_b32 s0, v115, 0
	v_readlane_b32 s1, v115, 1
	v_readlane_b32 s2, v115, 2
	v_readlane_b32 s3, v115, 3
	v_readlane_b32 s4, v115, 4
	v_readlane_b32 s5, v115, 5
	v_readlane_b32 s6, v115, 6
	v_readlane_b32 s7, v115, 7
	v_readlane_b32 s8, v115, 8
	v_readlane_b32 s9, v115, 9
	v_readlane_b32 s10, v115, 10
	v_readlane_b32 s11, v115, 11
	v_readlane_b32 s12, v115, 12
	v_readlane_b32 s13, v115, 13
	v_readlane_b32 s14, v115, 14
	v_readlane_b32 s15, v115, 15
	v_readlane_b32 s16, v115, 16
	v_readlane_b32 s17, v115, 17
	v_readlane_b32 s18, v115, 18
	v_readlane_b32 s19, v115, 19
	v_readlane_b32 s20, v115, 20
	v_readlane_b32 s21, v115, 21
	v_readlane_b32 s22, v115, 22
	v_readlane_b32 s23, v115, 23
	v_readlane_b32 s24, v115, 24
	v_readlane_b32 s25, v115, 25
	v_readlane_b32 s26, v115, 26
	v_readlane_b32 s27, v115, 27
	v_readlane_b32 s28, v115, 28
	v_readlane_b32 s29, v115, 29
	v_readlane_b32 s30, v115, 30
	v_readlane_b32 s31, v115, 31
	v_readlane_b32 s32, v115, 32
	v_readlane_b32 s33, v115, 33
	v_readlane_b32 s34, v115, 34
	v_readlane_b32 s35, v115, 35
	v_readlane_b32 s36, v115, 36
	v_readlane_b32 s37, v115, 37
	v_readlane_b32 s38, v115, 38
	v_readlane_b32 s39, v115, 39
	v_readlane_b32 s40, v115, 40
	v_readlane_b32 s41, v115, 41
	v_readlane_b32 s42, v115, 42
	v_readlane_b32 s43, v115, 43
	v_readlane_b32 s44, v115, 44
	v_readlane_b32 s45, v115, 45
	v_readlane_b32 s46, v115, 46
	v_readlane_b32 s47, v115, 47
	s_bitcmp1_b32 s99, 3
	s_cbranch_scc0 .Lp2_done
	s_mov_b32 s98, 0x10401
	s_branch .Lp2_na
.Lp2_done:
.LBB0_1107:
	v_mov_b32_e32 v1, v225
	v_readlane_b32 s0, v252, 58
	s_nop 1
	v_add_u32_e32 v0, s0, v1
	s_mov_b32 s0, 0x80000
	v_cmp_gt_i32_e32 vcc, s0, v0
	s_and_saveexec_b64 s[0:1], vcc
	s_cbranch_execz .LBB0_1114
	v_readlane_b32 s2, v252, 36
	v_and_b32_e32 v1, 31, v1
	v_readlane_b32 s36, v254, 17
	v_readlane_b32 s3, v252, 37
	s_add_u32 s2, s2, s28
	v_lshlrev_b32_e32 v144, 2, v1
	v_readlane_b32 s37, v254, 18
	v_ashrrev_i32_e32 v1, 31, v0
	s_addc_u32 s3, s3, s29
	v_lshl_add_u64 v[2:3], s[36:37], 0, v[144:145]
	v_lshl_add_u64 v[4:5], v[0:1], 2, s[2:3]
	s_mov_b64 s[2:3], 0
	v_readlane_b32 s38, v254, 19
	v_readlane_b32 s39, v254, 20
	v_readlane_b32 s40, v254, 21
	v_readlane_b32 s41, v254, 22
	v_readlane_b32 s42, v254, 23
	v_readlane_b32 s43, v254, 24
	v_readlane_b32 s44, v254, 25
	v_readlane_b32 s45, v254, 26
	v_readlane_b32 s46, v254, 27
	v_readlane_b32 s47, v254, 28
	v_readlane_b32 s48, v254, 29
	v_readlane_b32 s49, v254, 30
	v_readlane_b32 s50, v254, 31
	v_readlane_b32 s51, v254, 32
	s_branch .LBB0_1110
